# natten masked tile: relative-position bias fed as MFMA C operand (S=QK^T+bias in one pass), 40 v_add and 14 LDS loads per tile removed
# baseline (speedup 1.0000x reference)
.LBB0_347:
	s_bitcmp1_b32 s85, 0
	s_cselect_b32 s3, 0x2c00, 0
	s_cmp_gt_i32 s85, s97
	s_mov_b64 s[86:87], -1
	s_cbranch_scc1 .LBB0_435
	v_add_u32_e32 v2, s85, v195
	v_cmp_ge_u32_e32 vcc, v2, v194
	v_cmp_lt_u32_e64 s[86:87], v2, v214
	v_mov_b32_e32 v221, v163
	v_mov_b32_e32 v166, v0
	v_mov_b32_e32 v222, v220
	v_mov_b32_e32 v162, v219
	s_and_b64 vcc, vcc, s[86:87]
	s_and_saveexec_b64 s[86:87], vcc
	s_cbranch_execz .LBB0_434
	v_lshl_add_u32 v162, s3, 1, v215
	v_mov_b32_e32 v189, 0xff800000
	ds_read2_b32 v[168:169], v218 offset0:8 offset1:9
	ds_read2_b32 v[170:171], v218 offset0:10 offset1:11
	ds_read2_b32 v[172:173], v218 offset0:16 offset1:17
	ds_read2_b32 v[174:175], v218 offset0:18 offset1:19
	ds_read2_b32 v[176:177], v218 offset0:24 offset1:25
	ds_read2_b32 v[178:179], v218 offset0:26 offset1:27
	ds_read2_b32 v[180:181], v218 offset0:32 offset1:33
	ds_read2_b32 v[182:183], v218 offset0:34 offset1:35
	ds_read2_b32 v[22:23], v218 offset0:40 offset1:41
	ds_read2_b32 v[24:25], v218 offset0:42 offset1:43
	ds_read2_b32 v[18:19], v218 offset0:0 offset1:1
	ds_read2_b32 v[20:21], v218 offset0:2 offset1:3
	ds_read_b128 v[2:5], v162
	ds_read_b128 v[184:187], v162 offset:32
	ds_read_b128 v[54:57], v192 offset:47104
	ds_read_b128 v[58:61], v192 offset:47136
	s_waitcnt lgkmcnt(3)
	v_mfma_f32_32x32x16_bf16 v[38:53], v[2:5], v[130:133], v[168:183]
	s_waitcnt lgkmcnt(1)
	v_mfma_f32_32x32x16_bf16 v[6:21], v[2:5], v[54:57], v[6:21]
	ds_read_b128 v[2:5], v162 offset:64
	ds_read_b128 v[62:65], v192 offset:47168
	v_mfma_f32_32x32x16_bf16 v[38:53], v[184:187], v[134:137], v[38:53]
	s_waitcnt lgkmcnt(2)
	v_mfma_f32_32x32x16_bf16 v[6:21], v[184:187], v[58:61], v[6:21]
	s_waitcnt lgkmcnt(1)
	v_mfma_f32_32x32x16_bf16 v[38:53], v[2:5], v[138:141], v[38:53]
	s_waitcnt lgkmcnt(0)
	v_mfma_f32_32x32x16_bf16 v[6:21], v[2:5], v[62:65], v[6:21]
	ds_read_b128 v[2:5], v162 offset:96
	ds_read_b128 v[164:167], v192 offset:47200
	s_waitcnt lgkmcnt(1)
	v_mfma_f32_32x32x16_bf16 v[38:53], v[2:5], v[142:145], v[38:53]
	s_waitcnt lgkmcnt(0)
	v_mfma_f32_32x32x16_bf16 v[6:21], v[2:5], v[164:167], v[6:21]
	ds_read_b128 v[2:5], v162 offset:4608
	s_waitcnt lgkmcnt(0)
	v_mfma_f32_32x32x16_bf16 v[22:37], v[2:5], v[130:133], v[22:37]
	v_mfma_f32_32x32x16_bf16 v[2:17], v[2:5], v[54:57], v[168:183]
	ds_read_b128 v[54:57], v162 offset:4640
	s_waitcnt lgkmcnt(0)
	v_mfma_f32_32x32x16_bf16 v[22:37], v[54:57], v[134:137], v[22:37]
	v_mfma_f32_32x32x16_bf16 v[2:17], v[54:57], v[58:61], v[2:17]
	ds_read_b128 v[54:57], v162 offset:4672
	s_waitcnt lgkmcnt(0)
	v_mfma_f32_32x32x16_bf16 v[22:37], v[54:57], v[138:141], v[22:37]
	v_mfma_f32_32x32x16_bf16 v[2:17], v[54:57], v[62:65], v[2:17]
	ds_read_b128 v[54:57], v162 offset:4704
	s_waitcnt lgkmcnt(0)
	v_mfma_f32_32x32x16_bf16 v[22:37], v[54:57], v[142:145], v[22:37]
	v_mfma_f32_32x32x16_bf16 v[2:17], v[54:57], v[164:167], v[2:17]
	v_cndmask_b32_e64 v164, v189, v46, s[18:19]
	v_cndmask_b32_e64 v162, v189, v47, s[20:21]
	v_cndmask_b32_e64 v177, v189, v48, s[22:23]
	v_cndmask_b32_e64 v178, v189, v49, s[24:25]
	v_cndmask_b32_e64 v179, v189, v50, s[26:27]
	v_cndmask_b32_e64 v166, v189, v51, s[28:29]
	v_cndmask_b32_e64 v181, v189, v52, s[30:31]
	v_cndmask_b32_e64 v182, v189, v53, s[34:35]
	s_nop 2
	v_cndmask_b32_e64 v27, v189, v38, s[0:1]
	v_cndmask_b32_e64 v26, v189, v39, s[4:5]
	v_cndmask_b32_e64 v29, v189, v40, s[6:7]
	v_cndmask_b32_e64 v28, v189, v41, s[8:9]
	v_cndmask_b32_e64 v31, v189, v42, s[10:11]
	v_cndmask_b32_e64 v30, v189, v43, s[12:13]
	v_cndmask_b32_e64 v33, v189, v44, s[14:15]
	v_cndmask_b32_e64 v32, v189, v45, s[16:17]
	v_cndmask_b32_e64 v183, v189, v22, s[36:37]
	v_cndmask_b32_e64 v184, v189, v23, s[38:39]
	v_cndmask_b32_e64 v185, v189, v24, s[40:41]
	v_cndmask_b32_e64 v23, v189, v25, s[42:43]
	v_and_b32_e32 v24, 64, v200
	v_xor_b32_e32 v22, 32, v200
	v_add_u32_e32 v24, 64, v24
	v_cmp_lt_i32_e32 vcc, v22, v24
	s_nop 1
	v_cndmask_b32_e32 v22, v200, v22, vcc
	v_lshlrev_b32_e32 v22, 2, v22
	v_max3_f32 v24, v27, v26, v29
	v_max3_f32 v24, v24, v28, v31
	v_max3_f32 v24, v24, v30, v33
	v_max3_f32 v24, v24, v32, v164
	v_max3_f32 v24, v24, v162, v177
	v_max3_f32 v24, v24, v178, v179
	v_max3_f32 v24, v24, v166, v181
	v_max3_f32 v24, v24, v182, v183
	v_max3_f32 v24, v24, v184, v185
	s_mov_b32 s88, 0xff800000
	v_max3_f32 v24, v24, v23, s88
	ds_bpermute_b32 v25, v22, v24
	s_waitcnt lgkmcnt(0)
	v_max_f32_e32 v25, v25, v25
	v_max_f32_e32 v24, v24, v25
	v_add_f32_e32 v25, 0xc1000000, v24
	v_cmp_gt_f32_e32 vcc, v25, v163
	v_mov_b32_e32 v165, v220
	v_mov_b32_e32 v221, v163
	s_cbranch_vccz .LBB0_391
	v_max_f32_e32 v24, v24, v24
	v_max_f32_e32 v25, v163, v163
	v_max_f32_e32 v221, v25, v24
	v_sub_f32_e32 v24, v163, v221
	v_exp_f32_e32 v24, v24
	s_nop 0
	v_mul_f32_e32 v165, v220, v24
	v_pk_mul_f32 v[128:129], v[128:129], v[24:25] op_sel_hi:[1,0]
	v_pk_mul_f32 v[126:127], v[126:127], v[24:25] op_sel_hi:[1,0]
	v_pk_mul_f32 v[124:125], v[124:125], v[24:25] op_sel_hi:[1,0]
	v_pk_mul_f32 v[122:123], v[122:123], v[24:25] op_sel_hi:[1,0]
	v_pk_mul_f32 v[120:121], v[120:121], v[24:25] op_sel_hi:[1,0]
	v_pk_mul_f32 v[118:119], v[118:119], v[24:25] op_sel_hi:[1,0]
	v_pk_mul_f32 v[116:117], v[116:117], v[24:25] op_sel_hi:[1,0]
	v_pk_mul_f32 v[114:115], v[114:115], v[24:25] op_sel_hi:[1,0]
	v_pk_mul_f32 v[112:113], v[112:113], v[24:25] op_sel_hi:[1,0]
	v_pk_mul_f32 v[110:111], v[110:111], v[24:25] op_sel_hi:[1,0]
	v_pk_mul_f32 v[108:109], v[108:109], v[24:25] op_sel_hi:[1,0]
	v_pk_mul_f32 v[106:107], v[106:107], v[24:25] op_sel_hi:[1,0]
	v_pk_mul_f32 v[104:105], v[104:105], v[24:25] op_sel_hi:[1,0]
	v_pk_mul_f32 v[102:103], v[102:103], v[24:25] op_sel_hi:[1,0]
	v_pk_mul_f32 v[100:101], v[100:101], v[24:25] op_sel_hi:[1,0]
	v_pk_mul_f32 v[98:99], v[98:99], v[24:25] op_sel_hi:[1,0]
.LBB0_391:
	v_sub_f32_e32 v24, v27, v221
	v_exp_f32_e32 v167, v24
	v_sub_f32_e32 v24, v26, v221
	v_exp_f32_e32 v168, v24
	v_sub_f32_e32 v24, v29, v221
	v_exp_f32_e32 v169, v24
	v_sub_f32_e32 v24, v28, v221
	v_exp_f32_e32 v170, v24
	v_sub_f32_e32 v24, v31, v221
	v_exp_f32_e32 v171, v24
	v_sub_f32_e32 v24, v30, v221
	v_exp_f32_e32 v172, v24
	v_sub_f32_e32 v24, v33, v221
	v_exp_f32_e32 v173, v24
	v_sub_f32_e32 v24, v32, v221
	v_exp_f32_e32 v174, v24
	v_sub_f32_e32 v24, v164, v221
	v_exp_f32_e32 v175, v24
	v_sub_f32_e32 v24, v162, v221
	v_lshl_add_u32 v180, s3, 1, v216
	v_exp_f32_e32 v176, v24
	v_sub_f32_e32 v24, v177, v221
	v_exp_f32_e32 v177, v24
	v_sub_f32_e32 v24, v178, v221
	v_add_u32_e32 v162, 0x3000, v180
	v_exp_f32_e32 v178, v24
	ds_read2_b64 v[24:27], v162 offset0:128 offset1:130
	v_sub_f32_e32 v28, v179, v221
	v_exp_f32_e32 v179, v28
	v_cvt_pk_bf16_f32 v28, v167, v168
	v_cvt_pk_bf16_f32 v29, v169, v170
	v_cvt_pk_bf16_f32 v30, v171, v172
	v_cvt_pk_bf16_f32 v31, v173, v174
	v_add_u32_e32 v164, 0x4000, v180
	ds_read2_b64 v[186:189], v164 offset0:192 offset1:194
	s_waitcnt lgkmcnt(1)
	v_mfma_f32_32x32x16_bf16 v[114:129], v[24:27], v[28:31], v[114:129]
	v_sub_f32_e32 v24, v166, v221
	v_exp_f32_e32 v180, v24
	v_sub_f32_e32 v24, v181, v221
	v_exp_f32_e32 v181, v24
	v_sub_f32_e32 v24, v182, v221
	v_exp_f32_e32 v182, v24
	ds_read2_b64 v[24:27], v162 offset0:132 offset1:134
	s_waitcnt lgkmcnt(1)
	v_mfma_f32_32x32x16_bf16 v[98:113], v[186:189], v[28:31], v[98:113]
	v_sub_f32_e32 v28, v183, v221
	v_exp_f32_e32 v183, v28
	v_cvt_pk_bf16_f32 v28, v175, v176
	v_cvt_pk_bf16_f32 v29, v177, v178
	v_cvt_pk_bf16_f32 v30, v179, v180
	v_cvt_pk_bf16_f32 v31, v181, v182
	ds_read2_b64 v[222:225], v164 offset0:196 offset1:198
	v_sub_f32_e32 v23, v23, v221
	s_waitcnt lgkmcnt(1)
	v_mfma_f32_32x32x16_bf16 v[114:129], v[24:27], v[28:31], v[114:129]
	v_sub_f32_e32 v24, v184, v221
	v_exp_f32_e32 v184, v24
	v_sub_f32_e32 v24, v185, v221
	v_exp_f32_e32 v185, v24
	ds_read2_b64 v[24:27], v162 offset0:136 offset1:138
	v_exp_f32_e32 v186, v23
	v_sub_f32_e32 v23, 0xff800000, v221
	v_exp_f32_e32 v187, v23
	s_waitcnt lgkmcnt(1)
	v_mfma_f32_32x32x16_bf16 v[98:113], v[222:225], v[28:31], v[98:113]
	v_cvt_pk_bf16_f32 v28, v183, v184
	v_cvt_pk_bf16_f32 v29, v185, v186
	v_cvt_pk_bf16_f32 v30, v187, v187
	v_mov_b32_e32 v31, v30
	v_mov_b32_e32 v188, 0xff800000
	s_waitcnt lgkmcnt(0)
	v_mfma_f32_32x32x16_bf16 v[114:129], v[24:27], v[28:31], v[114:129]
	ds_read2_b64 v[24:27], v164 offset0:200 offset1:202
	s_waitcnt lgkmcnt(0)
	v_mfma_f32_32x32x16_bf16 v[98:113], v[24:27], v[28:31], v[98:113]
	v_mov_b32_e32 v23, 0xff800000
	v_cndmask_b32_e64 v189, v23, v18, s[44:45]
	v_cndmask_b32_e64 v188, v23, v19, s[46:47]
	v_cndmask_b32_e64 v209, v23, v20, s[48:49]
	v_cndmask_b32_e64 v208, v23, v21, s[50:51]
	v_cndmask_b32_e64 v225, v23, v2, s[52:53]
	v_cndmask_b32_e64 v223, v23, v3, s[54:55]
	v_cndmask_b32_e64 v233, v23, v4, s[56:57]
	v_cndmask_b32_e64 v231, v23, v5, s[58:59]
	v_cndmask_b32_e64 v237, v23, v6, s[60:61]
	v_cndmask_b32_e64 v212, v23, v7, s[62:63]
	v_cndmask_b32_e64 v227, v23, v8, s[64:65]
	v_cndmask_b32_e64 v224, v23, v9, s[66:67]
	v_cndmask_b32_e64 v235, v23, v10, s[68:69]
	v_cndmask_b32_e64 v229, v23, v11, s[70:71]
	v_cndmask_b32_e64 v234, v23, v12, s[72:73]
	v_cndmask_b32_e64 v226, v23, v13, s[74:75]
	v_cndmask_b32_e64 v230, v23, v14, s[76:77]
	v_cndmask_b32_e64 v228, v23, v15, s[78:79]
	v_cndmask_b32_e64 v236, v23, v16, s[80:81]
	v_cndmask_b32_e64 v232, v23, v17, s[82:83]
	v_max3_f32 v2, v189, s88, v188
	v_max3_f32 v2, v2, v209, v208
	v_max3_f32 v2, v2, v225, v223
	v_max3_f32 v2, v2, v233, v231
	v_max3_f32 v2, v2, v237, v212
	v_max3_f32 v2, v2, v227, v224
	v_max3_f32 v2, v2, v235, v229
	v_max3_f32 v2, v2, v234, v226
	v_max3_f32 v2, v2, v230, v228
	v_max3_f32 v2, v2, v236, v232
	ds_bpermute_b32 v3, v22, v2
	s_waitcnt lgkmcnt(0)
	v_max_f32_e32 v3, v3, v3
	v_max_f32_e32 v222, v2, v3
	v_add_f32_e32 v238, 0xc1000000, v222
	v_cmp_gt_f32_e32 vcc, v238, v0
	v_mov_b32_e32 v238, v219
	v_mov_b32_e32 v166, v0
	s_cbranch_vccz .LBB0_433
	v_max_f32_e32 v2, v222, v222
	v_max_f32_e32 v3, v0, v0
	v_max_f32_e32 v166, v3, v2
	v_sub_f32_e32 v2, v0, v166
	v_exp_f32_e32 v2, v2
	s_nop 0
	v_mul_f32_e32 v238, v219, v2
	v_pk_mul_f32 v[96:97], v[96:97], v[2:3] op_sel_hi:[1,0]
	v_pk_mul_f32 v[94:95], v[94:95], v[2:3] op_sel_hi:[1,0]
	v_pk_mul_f32 v[92:93], v[92:93], v[2:3] op_sel_hi:[1,0]
	v_pk_mul_f32 v[90:91], v[90:91], v[2:3] op_sel_hi:[1,0]
	v_pk_mul_f32 v[88:89], v[88:89], v[2:3] op_sel_hi:[1,0]
	v_pk_mul_f32 v[86:87], v[86:87], v[2:3] op_sel_hi:[1,0]
	v_pk_mul_f32 v[84:85], v[84:85], v[2:3] op_sel_hi:[1,0]
	v_pk_mul_f32 v[82:83], v[82:83], v[2:3] op_sel_hi:[1,0]
	v_pk_mul_f32 v[80:81], v[80:81], v[2:3] op_sel_hi:[1,0]
	v_pk_mul_f32 v[78:79], v[78:79], v[2:3] op_sel_hi:[1,0]
	v_pk_mul_f32 v[76:77], v[76:77], v[2:3] op_sel_hi:[1,0]
	v_pk_mul_f32 v[74:75], v[74:75], v[2:3] op_sel_hi:[1,0]
	v_pk_mul_f32 v[72:73], v[72:73], v[2:3] op_sel_hi:[1,0]
	v_pk_mul_f32 v[70:71], v[70:71], v[2:3] op_sel_hi:[1,0]
	v_pk_mul_f32 v[68:69], v[68:69], v[2:3] op_sel_hi:[1,0]
	v_pk_mul_f32 v[66:67], v[66:67], v[2:3] op_sel_hi:[1,0]
